# mid q-up/kv-up row-scaled rms-norm epilogue loops rewritten: all 32 row sums first (two lanes per row, packed fma), one rsqrt, row scale folded into the per-row factor, rows scaled via v_readlane
# speedup vs baseline: 1.0076x; 1.0076x over previous
.LBB0_1152:
	v_and_b32_e32 v199, 63, v208
	v_lshlrev_b32_e32 v198, 3, v199
	v_sub_u32_e32 v198, v8, v198
	v_lshrrev_b32_e32 v200, 1, v199
	v_and_b32_e32 v199, 1, v199
	v_mul_u32_u24_e32 v200, 0x204, v200
	v_lshl_add_u32 v200, v199, 8, v200
	v_add_u32_e32 v198, v198, v200
	v_mov_b32_e32 v194, 0
	v_mov_b32_e32 v195, 0
	v_mov_b32_e32 v196, 0
	v_mov_b32_e32 v197, 0
	v_and_b32_e32 v204, 63, v208
	v_lshrrev_b32_e32 v204, 1, v204
	v_lshl_add_u32 v204, v204, 2, v9
	ds_read_b32 v204, v204
	ds_read2_b32 v[222:223], v198 offset0:0 offset1:1
	ds_read2_b32 v[224:225], v198 offset0:2 offset1:3
	ds_read2_b32 v[226:227], v198 offset0:4 offset1:5
	ds_read2_b32 v[228:229], v198 offset0:6 offset1:7
	ds_read2_b32 v[230:231], v198 offset0:8 offset1:9
	ds_read2_b32 v[232:233], v198 offset0:10 offset1:11
	ds_read2_b32 v[234:235], v198 offset0:12 offset1:13
	ds_read2_b32 v[236:237], v198 offset0:14 offset1:15
	ds_read2_b32 v[238:239], v198 offset0:16 offset1:17
	ds_read2_b32 v[240:241], v198 offset0:18 offset1:19
	ds_read2_b32 v[242:243], v198 offset0:20 offset1:21
	ds_read2_b32 v[244:245], v198 offset0:22 offset1:23
	s_waitcnt lgkmcnt(11)
	v_pk_fma_f32 v[194:195], v[222:223], v[222:223], v[194:195]
	ds_read2_b32 v[246:247], v198 offset0:24 offset1:25
	s_waitcnt lgkmcnt(11)
	v_pk_fma_f32 v[196:197], v[224:225], v[224:225], v[196:197]
	ds_read2_b32 v[248:249], v198 offset0:26 offset1:27
	s_waitcnt lgkmcnt(11)
	v_pk_fma_f32 v[194:195], v[226:227], v[226:227], v[194:195]
	ds_read2_b32 v[250:251], v198 offset0:28 offset1:29
	s_waitcnt lgkmcnt(11)
	v_pk_fma_f32 v[196:197], v[228:229], v[228:229], v[196:197]
	ds_read2_b32 v[252:253], v198 offset0:30 offset1:31
	s_waitcnt lgkmcnt(11)
	v_pk_fma_f32 v[194:195], v[230:231], v[230:231], v[194:195]
	ds_read2_b32 v[222:223], v198 offset0:32 offset1:33
	s_waitcnt lgkmcnt(11)
	v_pk_fma_f32 v[196:197], v[232:233], v[232:233], v[196:197]
	ds_read2_b32 v[224:225], v198 offset0:34 offset1:35
	s_waitcnt lgkmcnt(11)
	v_pk_fma_f32 v[194:195], v[234:235], v[234:235], v[194:195]
	ds_read2_b32 v[226:227], v198 offset0:36 offset1:37
	s_waitcnt lgkmcnt(11)
	v_pk_fma_f32 v[196:197], v[236:237], v[236:237], v[196:197]
	ds_read2_b32 v[228:229], v198 offset0:38 offset1:39
	s_waitcnt lgkmcnt(11)
	v_pk_fma_f32 v[194:195], v[238:239], v[238:239], v[194:195]
	ds_read2_b32 v[230:231], v198 offset0:40 offset1:41
	s_waitcnt lgkmcnt(11)
	v_pk_fma_f32 v[196:197], v[240:241], v[240:241], v[196:197]
	ds_read2_b32 v[232:233], v198 offset0:42 offset1:43
	s_waitcnt lgkmcnt(11)
	v_pk_fma_f32 v[194:195], v[242:243], v[242:243], v[194:195]
	ds_read2_b32 v[234:235], v198 offset0:44 offset1:45
	s_waitcnt lgkmcnt(11)
	v_pk_fma_f32 v[196:197], v[244:245], v[244:245], v[196:197]
	ds_read2_b32 v[236:237], v198 offset0:46 offset1:47
	s_waitcnt lgkmcnt(11)
	v_pk_fma_f32 v[194:195], v[246:247], v[246:247], v[194:195]
	ds_read2_b32 v[238:239], v198 offset0:48 offset1:49
	s_waitcnt lgkmcnt(11)
	v_pk_fma_f32 v[196:197], v[248:249], v[248:249], v[196:197]
	ds_read2_b32 v[240:241], v198 offset0:50 offset1:51
	s_waitcnt lgkmcnt(11)
	v_pk_fma_f32 v[194:195], v[250:251], v[250:251], v[194:195]
	ds_read2_b32 v[242:243], v198 offset0:52 offset1:53
	s_waitcnt lgkmcnt(11)
	v_pk_fma_f32 v[196:197], v[252:253], v[252:253], v[196:197]
	ds_read2_b32 v[244:245], v198 offset0:54 offset1:55
	s_waitcnt lgkmcnt(11)
	v_pk_fma_f32 v[194:195], v[222:223], v[222:223], v[194:195]
	ds_read2_b32 v[246:247], v198 offset0:56 offset1:57
	s_waitcnt lgkmcnt(11)
	v_pk_fma_f32 v[196:197], v[224:225], v[224:225], v[196:197]
	ds_read2_b32 v[248:249], v198 offset0:58 offset1:59
	s_waitcnt lgkmcnt(11)
	v_pk_fma_f32 v[194:195], v[226:227], v[226:227], v[194:195]
	ds_read2_b32 v[250:251], v198 offset0:60 offset1:61
	s_waitcnt lgkmcnt(11)
	v_pk_fma_f32 v[196:197], v[228:229], v[228:229], v[196:197]
	ds_read2_b32 v[252:253], v198 offset0:62 offset1:63
	s_waitcnt lgkmcnt(11)
	v_pk_fma_f32 v[194:195], v[230:231], v[230:231], v[194:195]
	s_waitcnt lgkmcnt(10)
	v_pk_fma_f32 v[196:197], v[232:233], v[232:233], v[196:197]
	s_waitcnt lgkmcnt(9)
	v_pk_fma_f32 v[194:195], v[234:235], v[234:235], v[194:195]
	s_waitcnt lgkmcnt(8)
	v_pk_fma_f32 v[196:197], v[236:237], v[236:237], v[196:197]
	s_waitcnt lgkmcnt(7)
	v_pk_fma_f32 v[194:195], v[238:239], v[238:239], v[194:195]
	s_waitcnt lgkmcnt(6)
	v_pk_fma_f32 v[196:197], v[240:241], v[240:241], v[196:197]
	s_waitcnt lgkmcnt(5)
	v_pk_fma_f32 v[194:195], v[242:243], v[242:243], v[194:195]
	s_waitcnt lgkmcnt(4)
	v_pk_fma_f32 v[196:197], v[244:245], v[244:245], v[196:197]
	s_waitcnt lgkmcnt(3)
	v_pk_fma_f32 v[194:195], v[246:247], v[246:247], v[194:195]
	s_waitcnt lgkmcnt(2)
	v_pk_fma_f32 v[196:197], v[248:249], v[248:249], v[196:197]
	s_waitcnt lgkmcnt(1)
	v_pk_fma_f32 v[194:195], v[250:251], v[250:251], v[194:195]
	s_waitcnt lgkmcnt(0)
	v_pk_fma_f32 v[196:197], v[252:253], v[252:253], v[196:197]
	s_nop 0
	v_pk_add_f32 v[194:195], v[194:195], v[196:197]
	s_nop 0
	v_add_f32_e32 v194, v194, v195
	s_nop 1
	v_add_f32_dpp v194, v194, v194 quad_perm:[1,0,3,2] row_mask:0xf bank_mask:0xf bound_ctrl:1
	v_mul_f32_e32 v194, v194, v204
	v_mul_f32_e32 v194, v194, v204
	v_fmamk_f32 v194, v194, 0x3c000000, v209
	v_mul_f32_e32 v195, 0x4b800000, v194
	v_cmp_gt_f32_e32 vcc, s52, v194
	s_nop 1
	v_cndmask_b32_e32 v194, v194, v195, vcc
	v_rsq_f32_e32 v194, v194
	s_nop 0
	v_mul_f32_e32 v195, 0x45800000, v194
	v_cndmask_b32_e32 v194, v194, v195, vcc
	v_mul_f32_e32 v194, v194, v204
	v_mov_b32_e32 v201, v8
	ds_read2_b32 v[222:223], v201 offset1:1
	ds_read2_b32 v[224:225], v201 offset0:129 offset1:130
	v_add_u32_e32 v201, 0x408, v201
	ds_read2_b32 v[226:227], v201 offset1:1
	ds_read2_b32 v[228:229], v201 offset0:129 offset1:130
	v_add_u32_e32 v201, 0x408, v201
	s_nop 0
	v_readlane_b32 s2, v194, 0
	v_readlane_b32 s100, v194, 2
	ds_read2_b32 v[230:231], v201 offset1:1
	ds_read2_b32 v[232:233], v201 offset0:129 offset1:130
	v_add_u32_e32 v201, 0x408, v201
	s_waitcnt lgkmcnt(4)
	v_pk_mul_f32 v[222:223], v[222:223], s[2:3] op_sel_hi:[1,0]
	v_pk_mul_f32 v[224:225], v[224:225], s[100:101] op_sel_hi:[1,0]
	v_readlane_b32 vcc_lo, v194, 4
	v_readlane_b32 s2, v194, 6
	v_pk_mul_f32 v[222:223], v[2:3], v[222:223]
	v_pk_mul_f32 v[224:225], v[2:3], v[224:225]
	v_cvt_pk_bf16_f32 v202, v222, v223
	v_cvt_pk_bf16_f32 v203, v224, v225
	global_store_dword v[4:5], v202, off
	v_lshl_add_u64 v[4:5], v[4:5], 0, s[90:91]
	global_store_dword v[4:5], v203, off
	v_lshl_add_u64 v[4:5], v[4:5], 0, s[90:91]
	ds_read2_b32 v[234:235], v201 offset1:1
	ds_read2_b32 v[236:237], v201 offset0:129 offset1:130
	v_add_u32_e32 v201, 0x408, v201
	s_waitcnt lgkmcnt(4)
	v_pk_mul_f32 v[226:227], v[226:227], vcc op_sel_hi:[1,0]
	v_pk_mul_f32 v[228:229], v[228:229], s[2:3] op_sel_hi:[1,0]
	v_readlane_b32 s100, v194, 8
	v_readlane_b32 vcc_lo, v194, 10
	v_pk_mul_f32 v[226:227], v[2:3], v[226:227]
	v_pk_mul_f32 v[228:229], v[2:3], v[228:229]
	v_cvt_pk_bf16_f32 v202, v226, v227
	v_cvt_pk_bf16_f32 v203, v228, v229
	global_store_dword v[4:5], v202, off
	v_lshl_add_u64 v[4:5], v[4:5], 0, s[90:91]
	global_store_dword v[4:5], v203, off
	v_lshl_add_u64 v[4:5], v[4:5], 0, s[90:91]
	ds_read2_b32 v[222:223], v201 offset1:1
	ds_read2_b32 v[224:225], v201 offset0:129 offset1:130
	v_add_u32_e32 v201, 0x408, v201
	s_waitcnt lgkmcnt(4)
	v_pk_mul_f32 v[230:231], v[230:231], s[100:101] op_sel_hi:[1,0]
	v_pk_mul_f32 v[232:233], v[232:233], vcc op_sel_hi:[1,0]
	v_readlane_b32 s2, v194, 12
	v_readlane_b32 s100, v194, 14
	v_pk_mul_f32 v[230:231], v[2:3], v[230:231]
	v_pk_mul_f32 v[232:233], v[2:3], v[232:233]
	v_cvt_pk_bf16_f32 v202, v230, v231
	v_cvt_pk_bf16_f32 v203, v232, v233
	global_store_dword v[4:5], v202, off
	v_lshl_add_u64 v[4:5], v[4:5], 0, s[90:91]
	global_store_dword v[4:5], v203, off
	v_lshl_add_u64 v[4:5], v[4:5], 0, s[90:91]
	ds_read2_b32 v[226:227], v201 offset1:1
	ds_read2_b32 v[228:229], v201 offset0:129 offset1:130
	v_add_u32_e32 v201, 0x408, v201
	s_waitcnt lgkmcnt(4)
	v_pk_mul_f32 v[234:235], v[234:235], s[2:3] op_sel_hi:[1,0]
	v_pk_mul_f32 v[236:237], v[236:237], s[100:101] op_sel_hi:[1,0]
	v_readlane_b32 vcc_lo, v194, 16
	v_readlane_b32 s2, v194, 18
	v_pk_mul_f32 v[234:235], v[2:3], v[234:235]
	v_pk_mul_f32 v[236:237], v[2:3], v[236:237]
	v_cvt_pk_bf16_f32 v202, v234, v235
	v_cvt_pk_bf16_f32 v203, v236, v237
	global_store_dword v[4:5], v202, off
	v_lshl_add_u64 v[4:5], v[4:5], 0, s[90:91]
	global_store_dword v[4:5], v203, off
	v_lshl_add_u64 v[4:5], v[4:5], 0, s[90:91]
	ds_read2_b32 v[230:231], v201 offset1:1
	ds_read2_b32 v[232:233], v201 offset0:129 offset1:130
	v_add_u32_e32 v201, 0x408, v201
	s_waitcnt lgkmcnt(4)
	v_pk_mul_f32 v[222:223], v[222:223], vcc op_sel_hi:[1,0]
	v_pk_mul_f32 v[224:225], v[224:225], s[2:3] op_sel_hi:[1,0]
	v_readlane_b32 s100, v194, 20
	v_readlane_b32 vcc_lo, v194, 22
	v_pk_mul_f32 v[222:223], v[2:3], v[222:223]
	v_pk_mul_f32 v[224:225], v[2:3], v[224:225]
	v_cvt_pk_bf16_f32 v202, v222, v223
	v_cvt_pk_bf16_f32 v203, v224, v225
	global_store_dword v[4:5], v202, off
	v_lshl_add_u64 v[4:5], v[4:5], 0, s[90:91]
	global_store_dword v[4:5], v203, off
	v_lshl_add_u64 v[4:5], v[4:5], 0, s[90:91]
	ds_read2_b32 v[234:235], v201 offset1:1
	ds_read2_b32 v[236:237], v201 offset0:129 offset1:130
	v_add_u32_e32 v201, 0x408, v201
	s_waitcnt lgkmcnt(4)
	v_pk_mul_f32 v[226:227], v[226:227], s[100:101] op_sel_hi:[1,0]
	v_pk_mul_f32 v[228:229], v[228:229], vcc op_sel_hi:[1,0]
	v_readlane_b32 s2, v194, 24
	v_readlane_b32 s100, v194, 26
	v_pk_mul_f32 v[226:227], v[2:3], v[226:227]
	v_pk_mul_f32 v[228:229], v[2:3], v[228:229]
	v_cvt_pk_bf16_f32 v202, v226, v227
	v_cvt_pk_bf16_f32 v203, v228, v229
	global_store_dword v[4:5], v202, off
	v_lshl_add_u64 v[4:5], v[4:5], 0, s[90:91]
	global_store_dword v[4:5], v203, off
	v_lshl_add_u64 v[4:5], v[4:5], 0, s[90:91]
	ds_read2_b32 v[222:223], v201 offset1:1
	ds_read2_b32 v[224:225], v201 offset0:129 offset1:130
	v_add_u32_e32 v201, 0x408, v201
	s_waitcnt lgkmcnt(4)
	v_pk_mul_f32 v[230:231], v[230:231], s[2:3] op_sel_hi:[1,0]
	v_pk_mul_f32 v[232:233], v[232:233], s[100:101] op_sel_hi:[1,0]
	v_readlane_b32 vcc_lo, v194, 28
	v_readlane_b32 s2, v194, 30
	v_pk_mul_f32 v[230:231], v[2:3], v[230:231]
	v_pk_mul_f32 v[232:233], v[2:3], v[232:233]
	v_cvt_pk_bf16_f32 v202, v230, v231
	v_cvt_pk_bf16_f32 v203, v232, v233
	global_store_dword v[4:5], v202, off
	v_lshl_add_u64 v[4:5], v[4:5], 0, s[90:91]
	global_store_dword v[4:5], v203, off
	v_lshl_add_u64 v[4:5], v[4:5], 0, s[90:91]
	ds_read2_b32 v[226:227], v201 offset1:1
	ds_read2_b32 v[228:229], v201 offset0:129 offset1:130
	v_add_u32_e32 v201, 0x408, v201
	s_waitcnt lgkmcnt(4)
	v_pk_mul_f32 v[234:235], v[234:235], vcc op_sel_hi:[1,0]
	v_pk_mul_f32 v[236:237], v[236:237], s[2:3] op_sel_hi:[1,0]
	v_readlane_b32 s100, v194, 32
	v_readlane_b32 vcc_lo, v194, 34
	v_pk_mul_f32 v[234:235], v[2:3], v[234:235]
	v_pk_mul_f32 v[236:237], v[2:3], v[236:237]
	v_cvt_pk_bf16_f32 v202, v234, v235
	v_cvt_pk_bf16_f32 v203, v236, v237
	global_store_dword v[4:5], v202, off
	v_lshl_add_u64 v[4:5], v[4:5], 0, s[90:91]
	global_store_dword v[4:5], v203, off
	v_lshl_add_u64 v[4:5], v[4:5], 0, s[90:91]
	ds_read2_b32 v[230:231], v201 offset1:1
	ds_read2_b32 v[232:233], v201 offset0:129 offset1:130
	v_add_u32_e32 v201, 0x408, v201
	s_waitcnt lgkmcnt(4)
	v_pk_mul_f32 v[222:223], v[222:223], s[100:101] op_sel_hi:[1,0]
	v_pk_mul_f32 v[224:225], v[224:225], vcc op_sel_hi:[1,0]
	v_readlane_b32 s2, v194, 36
	v_readlane_b32 s100, v194, 38
	v_pk_mul_f32 v[222:223], v[2:3], v[222:223]
	v_pk_mul_f32 v[224:225], v[2:3], v[224:225]
	v_cvt_pk_bf16_f32 v202, v222, v223
	v_cvt_pk_bf16_f32 v203, v224, v225
	global_store_dword v[4:5], v202, off
	v_lshl_add_u64 v[4:5], v[4:5], 0, s[90:91]
	global_store_dword v[4:5], v203, off
	v_lshl_add_u64 v[4:5], v[4:5], 0, s[90:91]
	ds_read2_b32 v[234:235], v201 offset1:1
	ds_read2_b32 v[236:237], v201 offset0:129 offset1:130
	v_add_u32_e32 v201, 0x408, v201
	s_waitcnt lgkmcnt(4)
	v_pk_mul_f32 v[226:227], v[226:227], s[2:3] op_sel_hi:[1,0]
	v_pk_mul_f32 v[228:229], v[228:229], s[100:101] op_sel_hi:[1,0]
	v_readlane_b32 vcc_lo, v194, 40
	v_readlane_b32 s2, v194, 42
	v_pk_mul_f32 v[226:227], v[2:3], v[226:227]
	v_pk_mul_f32 v[228:229], v[2:3], v[228:229]
	v_cvt_pk_bf16_f32 v202, v226, v227
	v_cvt_pk_bf16_f32 v203, v228, v229
	global_store_dword v[4:5], v202, off
	v_lshl_add_u64 v[4:5], v[4:5], 0, s[90:91]
	global_store_dword v[4:5], v203, off
	v_lshl_add_u64 v[4:5], v[4:5], 0, s[90:91]
	ds_read2_b32 v[222:223], v201 offset1:1
	ds_read2_b32 v[224:225], v201 offset0:129 offset1:130
	v_add_u32_e32 v201, 0x408, v201
	s_waitcnt lgkmcnt(4)
	v_pk_mul_f32 v[230:231], v[230:231], vcc op_sel_hi:[1,0]
	v_pk_mul_f32 v[232:233], v[232:233], s[2:3] op_sel_hi:[1,0]
	v_readlane_b32 s100, v194, 44
	v_readlane_b32 vcc_lo, v194, 46
	v_pk_mul_f32 v[230:231], v[2:3], v[230:231]
	v_pk_mul_f32 v[232:233], v[2:3], v[232:233]
	v_cvt_pk_bf16_f32 v202, v230, v231
	v_cvt_pk_bf16_f32 v203, v232, v233
	global_store_dword v[4:5], v202, off
	v_lshl_add_u64 v[4:5], v[4:5], 0, s[90:91]
	global_store_dword v[4:5], v203, off
	v_lshl_add_u64 v[4:5], v[4:5], 0, s[90:91]
	ds_read2_b32 v[226:227], v201 offset1:1
	ds_read2_b32 v[228:229], v201 offset0:129 offset1:130
	v_add_u32_e32 v201, 0x408, v201
	s_waitcnt lgkmcnt(4)
	v_pk_mul_f32 v[234:235], v[234:235], s[100:101] op_sel_hi:[1,0]
	v_pk_mul_f32 v[236:237], v[236:237], vcc op_sel_hi:[1,0]
	v_readlane_b32 s2, v194, 48
	v_readlane_b32 s100, v194, 50
	v_pk_mul_f32 v[234:235], v[2:3], v[234:235]
	v_pk_mul_f32 v[236:237], v[2:3], v[236:237]
	v_cvt_pk_bf16_f32 v202, v234, v235
	v_cvt_pk_bf16_f32 v203, v236, v237
	global_store_dword v[4:5], v202, off
	v_lshl_add_u64 v[4:5], v[4:5], 0, s[90:91]
	global_store_dword v[4:5], v203, off
	v_lshl_add_u64 v[4:5], v[4:5], 0, s[90:91]
	ds_read2_b32 v[230:231], v201 offset1:1
	ds_read2_b32 v[232:233], v201 offset0:129 offset1:130
	v_add_u32_e32 v201, 0x408, v201
	s_waitcnt lgkmcnt(4)
	v_pk_mul_f32 v[222:223], v[222:223], s[2:3] op_sel_hi:[1,0]
	v_pk_mul_f32 v[224:225], v[224:225], s[100:101] op_sel_hi:[1,0]
	v_readlane_b32 vcc_lo, v194, 52
	v_readlane_b32 s2, v194, 54
	v_pk_mul_f32 v[222:223], v[2:3], v[222:223]
	v_pk_mul_f32 v[224:225], v[2:3], v[224:225]
	v_cvt_pk_bf16_f32 v202, v222, v223
	v_cvt_pk_bf16_f32 v203, v224, v225
	global_store_dword v[4:5], v202, off
	v_lshl_add_u64 v[4:5], v[4:5], 0, s[90:91]
	global_store_dword v[4:5], v203, off
	v_lshl_add_u64 v[4:5], v[4:5], 0, s[90:91]
	ds_read2_b32 v[234:235], v201 offset1:1
	ds_read2_b32 v[236:237], v201 offset0:129 offset1:130
	v_add_u32_e32 v201, 0x408, v201
	s_waitcnt lgkmcnt(4)
	v_pk_mul_f32 v[226:227], v[226:227], vcc op_sel_hi:[1,0]
	v_pk_mul_f32 v[228:229], v[228:229], s[2:3] op_sel_hi:[1,0]
	v_readlane_b32 s100, v194, 56
	v_readlane_b32 vcc_lo, v194, 58
	v_pk_mul_f32 v[226:227], v[2:3], v[226:227]
	v_pk_mul_f32 v[228:229], v[2:3], v[228:229]
	v_cvt_pk_bf16_f32 v202, v226, v227
	v_cvt_pk_bf16_f32 v203, v228, v229
	global_store_dword v[4:5], v202, off
	v_lshl_add_u64 v[4:5], v[4:5], 0, s[90:91]
	global_store_dword v[4:5], v203, off
	v_lshl_add_u64 v[4:5], v[4:5], 0, s[90:91]
	s_waitcnt lgkmcnt(2)
	v_pk_mul_f32 v[230:231], v[230:231], s[100:101] op_sel_hi:[1,0]
	v_pk_mul_f32 v[232:233], v[232:233], vcc op_sel_hi:[1,0]
	v_readlane_b32 s2, v194, 60
	v_readlane_b32 s100, v194, 62
	v_pk_mul_f32 v[230:231], v[2:3], v[230:231]
	v_pk_mul_f32 v[232:233], v[2:3], v[232:233]
	v_cvt_pk_bf16_f32 v202, v230, v231
	v_cvt_pk_bf16_f32 v203, v232, v233
	global_store_dword v[4:5], v202, off
	v_lshl_add_u64 v[4:5], v[4:5], 0, s[90:91]
	global_store_dword v[4:5], v203, off
	v_lshl_add_u64 v[4:5], v[4:5], 0, s[90:91]
	s_waitcnt lgkmcnt(0)
	v_pk_mul_f32 v[234:235], v[234:235], s[2:3] op_sel_hi:[1,0]
	v_pk_mul_f32 v[236:237], v[236:237], s[100:101] op_sel_hi:[1,0]
	s_nop 1
	v_pk_mul_f32 v[234:235], v[2:3], v[234:235]
	v_pk_mul_f32 v[236:237], v[2:3], v[236:237]
	v_cvt_pk_bf16_f32 v202, v234, v235
	v_cvt_pk_bf16_f32 v203, v236, v237
	global_store_dword v[4:5], v202, off
	v_lshl_add_u64 v[4:5], v[4:5], 0, s[90:91]
	global_store_dword v[4:5], v203, off
	v_lshl_add_u64 v[4:5], v[4:5], 0, s[90:91]
	s_movk_i32 s2, 0x4080
	s_branch .LBB0_1104

.LBB0_1207:
	v_and_b32_e32 v199, 63, v208
	v_lshlrev_b32_e32 v198, 3, v199
	v_sub_u32_e32 v198, v8, v198
	v_lshrrev_b32_e32 v200, 1, v199
	v_and_b32_e32 v199, 1, v199
	v_mul_u32_u24_e32 v200, 0x204, v200
	v_lshl_add_u32 v200, v199, 8, v200
	v_add_u32_e32 v198, v198, v200
	v_mov_b32_e32 v194, 0
	v_mov_b32_e32 v195, 0
	v_mov_b32_e32 v196, 0
	v_mov_b32_e32 v197, 0
	v_and_b32_e32 v204, 63, v208
	v_lshrrev_b32_e32 v204, 1, v204
	v_lshl_add_u32 v204, v204, 2, v9
	ds_read_b32 v204, v204
	ds_read2_b32 v[222:223], v198 offset0:0 offset1:1
	ds_read2_b32 v[224:225], v198 offset0:2 offset1:3
	ds_read2_b32 v[226:227], v198 offset0:4 offset1:5
	ds_read2_b32 v[228:229], v198 offset0:6 offset1:7
	ds_read2_b32 v[230:231], v198 offset0:8 offset1:9
	ds_read2_b32 v[232:233], v198 offset0:10 offset1:11
	ds_read2_b32 v[234:235], v198 offset0:12 offset1:13
	ds_read2_b32 v[236:237], v198 offset0:14 offset1:15
	ds_read2_b32 v[238:239], v198 offset0:16 offset1:17
	ds_read2_b32 v[240:241], v198 offset0:18 offset1:19
	ds_read2_b32 v[242:243], v198 offset0:20 offset1:21
	ds_read2_b32 v[244:245], v198 offset0:22 offset1:23
	s_waitcnt lgkmcnt(11)
	v_pk_fma_f32 v[194:195], v[222:223], v[222:223], v[194:195]
	ds_read2_b32 v[246:247], v198 offset0:24 offset1:25
	s_waitcnt lgkmcnt(11)
	v_pk_fma_f32 v[196:197], v[224:225], v[224:225], v[196:197]
	ds_read2_b32 v[248:249], v198 offset0:26 offset1:27
	s_waitcnt lgkmcnt(11)
	v_pk_fma_f32 v[194:195], v[226:227], v[226:227], v[194:195]
	ds_read2_b32 v[250:251], v198 offset0:28 offset1:29
	s_waitcnt lgkmcnt(11)
	v_pk_fma_f32 v[196:197], v[228:229], v[228:229], v[196:197]
	ds_read2_b32 v[252:253], v198 offset0:30 offset1:31
	s_waitcnt lgkmcnt(11)
	v_pk_fma_f32 v[194:195], v[230:231], v[230:231], v[194:195]
	ds_read2_b32 v[222:223], v198 offset0:32 offset1:33
	s_waitcnt lgkmcnt(11)
	v_pk_fma_f32 v[196:197], v[232:233], v[232:233], v[196:197]
	ds_read2_b32 v[224:225], v198 offset0:34 offset1:35
	s_waitcnt lgkmcnt(11)
	v_pk_fma_f32 v[194:195], v[234:235], v[234:235], v[194:195]
	ds_read2_b32 v[226:227], v198 offset0:36 offset1:37
	s_waitcnt lgkmcnt(11)
	v_pk_fma_f32 v[196:197], v[236:237], v[236:237], v[196:197]
	ds_read2_b32 v[228:229], v198 offset0:38 offset1:39
	s_waitcnt lgkmcnt(11)
	v_pk_fma_f32 v[194:195], v[238:239], v[238:239], v[194:195]
	ds_read2_b32 v[230:231], v198 offset0:40 offset1:41
	s_waitcnt lgkmcnt(11)
	v_pk_fma_f32 v[196:197], v[240:241], v[240:241], v[196:197]
	ds_read2_b32 v[232:233], v198 offset0:42 offset1:43
	s_waitcnt lgkmcnt(11)
	v_pk_fma_f32 v[194:195], v[242:243], v[242:243], v[194:195]
	ds_read2_b32 v[234:235], v198 offset0:44 offset1:45
	s_waitcnt lgkmcnt(11)
	v_pk_fma_f32 v[196:197], v[244:245], v[244:245], v[196:197]
	ds_read2_b32 v[236:237], v198 offset0:46 offset1:47
	s_waitcnt lgkmcnt(11)
	v_pk_fma_f32 v[194:195], v[246:247], v[246:247], v[194:195]
	ds_read2_b32 v[238:239], v198 offset0:48 offset1:49
	s_waitcnt lgkmcnt(11)
	v_pk_fma_f32 v[196:197], v[248:249], v[248:249], v[196:197]
	ds_read2_b32 v[240:241], v198 offset0:50 offset1:51
	s_waitcnt lgkmcnt(11)
	v_pk_fma_f32 v[194:195], v[250:251], v[250:251], v[194:195]
	ds_read2_b32 v[242:243], v198 offset0:52 offset1:53
	s_waitcnt lgkmcnt(11)
	v_pk_fma_f32 v[196:197], v[252:253], v[252:253], v[196:197]
	ds_read2_b32 v[244:245], v198 offset0:54 offset1:55
	s_waitcnt lgkmcnt(11)
	v_pk_fma_f32 v[194:195], v[222:223], v[222:223], v[194:195]
	ds_read2_b32 v[246:247], v198 offset0:56 offset1:57
	s_waitcnt lgkmcnt(11)
	v_pk_fma_f32 v[196:197], v[224:225], v[224:225], v[196:197]
	ds_read2_b32 v[248:249], v198 offset0:58 offset1:59
	s_waitcnt lgkmcnt(11)
	v_pk_fma_f32 v[194:195], v[226:227], v[226:227], v[194:195]
	ds_read2_b32 v[250:251], v198 offset0:60 offset1:61
	s_waitcnt lgkmcnt(11)
	v_pk_fma_f32 v[196:197], v[228:229], v[228:229], v[196:197]
	ds_read2_b32 v[252:253], v198 offset0:62 offset1:63
	s_waitcnt lgkmcnt(11)
	v_pk_fma_f32 v[194:195], v[230:231], v[230:231], v[194:195]
	s_waitcnt lgkmcnt(10)
	v_pk_fma_f32 v[196:197], v[232:233], v[232:233], v[196:197]
	s_waitcnt lgkmcnt(9)
	v_pk_fma_f32 v[194:195], v[234:235], v[234:235], v[194:195]
	s_waitcnt lgkmcnt(8)
	v_pk_fma_f32 v[196:197], v[236:237], v[236:237], v[196:197]
	s_waitcnt lgkmcnt(7)
	v_pk_fma_f32 v[194:195], v[238:239], v[238:239], v[194:195]
	s_waitcnt lgkmcnt(6)
	v_pk_fma_f32 v[196:197], v[240:241], v[240:241], v[196:197]
	s_waitcnt lgkmcnt(5)
	v_pk_fma_f32 v[194:195], v[242:243], v[242:243], v[194:195]
	s_waitcnt lgkmcnt(4)
	v_pk_fma_f32 v[196:197], v[244:245], v[244:245], v[196:197]
	s_waitcnt lgkmcnt(3)
	v_pk_fma_f32 v[194:195], v[246:247], v[246:247], v[194:195]
	s_waitcnt lgkmcnt(2)
	v_pk_fma_f32 v[196:197], v[248:249], v[248:249], v[196:197]
	s_waitcnt lgkmcnt(1)
	v_pk_fma_f32 v[194:195], v[250:251], v[250:251], v[194:195]
	s_waitcnt lgkmcnt(0)
	v_pk_fma_f32 v[196:197], v[252:253], v[252:253], v[196:197]
	s_nop 0
	v_pk_add_f32 v[194:195], v[194:195], v[196:197]
	s_nop 0
	v_add_f32_e32 v194, v194, v195
	s_nop 1
	v_add_f32_dpp v194, v194, v194 quad_perm:[1,0,3,2] row_mask:0xf bank_mask:0xf bound_ctrl:1
	v_cndmask_b32_e64 v204, v204, 1.0, s[2:3]
	v_mul_f32_e32 v194, v194, v204
	v_mul_f32_e32 v194, v194, v204
	v_fmamk_f32 v194, v194, 0x3c000000, v209
	v_mul_f32_e32 v195, 0x4b800000, v194
	v_cmp_gt_f32_e32 vcc, s52, v194
	s_nop 1
	v_cndmask_b32_e32 v194, v194, v195, vcc
	v_rsq_f32_e32 v194, v194
	s_nop 0
	v_mul_f32_e32 v195, 0x45800000, v194
	v_cndmask_b32_e32 v194, v194, v195, vcc
	v_mul_f32_e32 v194, v194, v204
	v_mov_b32_e32 v201, v8
	ds_read2_b32 v[222:223], v201 offset1:1
	ds_read2_b32 v[224:225], v201 offset0:129 offset1:130
	v_add_u32_e32 v201, 0x408, v201
	ds_read2_b32 v[226:227], v201 offset1:1
	ds_read2_b32 v[228:229], v201 offset0:129 offset1:130
	v_add_u32_e32 v201, 0x408, v201
	s_nop 0
	v_readlane_b32 s4, v194, 0
	v_readlane_b32 s100, v194, 2
	ds_read2_b32 v[230:231], v201 offset1:1
	ds_read2_b32 v[232:233], v201 offset0:129 offset1:130
	v_add_u32_e32 v201, 0x408, v201
	s_waitcnt lgkmcnt(4)
	v_pk_mul_f32 v[222:223], v[222:223], s[4:5] op_sel_hi:[1,0]
	v_pk_mul_f32 v[224:225], v[224:225], s[100:101] op_sel_hi:[1,0]
	v_readlane_b32 vcc_lo, v194, 4
	v_readlane_b32 s4, v194, 6
	v_pk_mul_f32 v[222:223], v[2:3], v[222:223]
	v_pk_mul_f32 v[224:225], v[2:3], v[224:225]
	v_cvt_pk_bf16_f32 v202, v222, v223
	v_cvt_pk_bf16_f32 v203, v224, v225
	global_store_dword v[4:5], v202, off
	v_lshl_add_u64 v[4:5], v[4:5], 0, s[90:91]
	global_store_dword v[4:5], v203, off
	v_lshl_add_u64 v[4:5], v[4:5], 0, s[90:91]
	ds_read2_b32 v[234:235], v201 offset1:1
	ds_read2_b32 v[236:237], v201 offset0:129 offset1:130
	v_add_u32_e32 v201, 0x408, v201
	s_waitcnt lgkmcnt(4)
	v_pk_mul_f32 v[226:227], v[226:227], vcc op_sel_hi:[1,0]
	v_pk_mul_f32 v[228:229], v[228:229], s[4:5] op_sel_hi:[1,0]
	v_readlane_b32 s100, v194, 8
	v_readlane_b32 vcc_lo, v194, 10
	v_pk_mul_f32 v[226:227], v[2:3], v[226:227]
	v_pk_mul_f32 v[228:229], v[2:3], v[228:229]
	v_cvt_pk_bf16_f32 v202, v226, v227
	v_cvt_pk_bf16_f32 v203, v228, v229
	global_store_dword v[4:5], v202, off
	v_lshl_add_u64 v[4:5], v[4:5], 0, s[90:91]
	global_store_dword v[4:5], v203, off
	v_lshl_add_u64 v[4:5], v[4:5], 0, s[90:91]
	ds_read2_b32 v[222:223], v201 offset1:1
	ds_read2_b32 v[224:225], v201 offset0:129 offset1:130
	v_add_u32_e32 v201, 0x408, v201
	s_waitcnt lgkmcnt(4)
	v_pk_mul_f32 v[230:231], v[230:231], s[100:101] op_sel_hi:[1,0]
	v_pk_mul_f32 v[232:233], v[232:233], vcc op_sel_hi:[1,0]
	v_readlane_b32 s4, v194, 12
	v_readlane_b32 s100, v194, 14
	v_pk_mul_f32 v[230:231], v[2:3], v[230:231]
	v_pk_mul_f32 v[232:233], v[2:3], v[232:233]
	v_cvt_pk_bf16_f32 v202, v230, v231
	v_cvt_pk_bf16_f32 v203, v232, v233
	global_store_dword v[4:5], v202, off
	v_lshl_add_u64 v[4:5], v[4:5], 0, s[90:91]
	global_store_dword v[4:5], v203, off
	v_lshl_add_u64 v[4:5], v[4:5], 0, s[90:91]
	ds_read2_b32 v[226:227], v201 offset1:1
	ds_read2_b32 v[228:229], v201 offset0:129 offset1:130
	v_add_u32_e32 v201, 0x408, v201
	s_waitcnt lgkmcnt(4)
	v_pk_mul_f32 v[234:235], v[234:235], s[4:5] op_sel_hi:[1,0]
	v_pk_mul_f32 v[236:237], v[236:237], s[100:101] op_sel_hi:[1,0]
	v_readlane_b32 vcc_lo, v194, 16
	v_readlane_b32 s4, v194, 18
	v_pk_mul_f32 v[234:235], v[2:3], v[234:235]
	v_pk_mul_f32 v[236:237], v[2:3], v[236:237]
	v_cvt_pk_bf16_f32 v202, v234, v235
	v_cvt_pk_bf16_f32 v203, v236, v237
	global_store_dword v[4:5], v202, off
	v_lshl_add_u64 v[4:5], v[4:5], 0, s[90:91]
	global_store_dword v[4:5], v203, off
	v_lshl_add_u64 v[4:5], v[4:5], 0, s[90:91]
	ds_read2_b32 v[230:231], v201 offset1:1
	ds_read2_b32 v[232:233], v201 offset0:129 offset1:130
	v_add_u32_e32 v201, 0x408, v201
	s_waitcnt lgkmcnt(4)
	v_pk_mul_f32 v[222:223], v[222:223], vcc op_sel_hi:[1,0]
	v_pk_mul_f32 v[224:225], v[224:225], s[4:5] op_sel_hi:[1,0]
	v_readlane_b32 s100, v194, 20
	v_readlane_b32 vcc_lo, v194, 22
	v_pk_mul_f32 v[222:223], v[2:3], v[222:223]
	v_pk_mul_f32 v[224:225], v[2:3], v[224:225]
	v_cvt_pk_bf16_f32 v202, v222, v223
	v_cvt_pk_bf16_f32 v203, v224, v225
	global_store_dword v[4:5], v202, off
	v_lshl_add_u64 v[4:5], v[4:5], 0, s[90:91]
	global_store_dword v[4:5], v203, off
	v_lshl_add_u64 v[4:5], v[4:5], 0, s[90:91]
	ds_read2_b32 v[234:235], v201 offset1:1
	ds_read2_b32 v[236:237], v201 offset0:129 offset1:130
	v_add_u32_e32 v201, 0x408, v201
	s_waitcnt lgkmcnt(4)
	v_pk_mul_f32 v[226:227], v[226:227], s[100:101] op_sel_hi:[1,0]
	v_pk_mul_f32 v[228:229], v[228:229], vcc op_sel_hi:[1,0]
	v_readlane_b32 s4, v194, 24
	v_readlane_b32 s100, v194, 26
	v_pk_mul_f32 v[226:227], v[2:3], v[226:227]
	v_pk_mul_f32 v[228:229], v[2:3], v[228:229]
	v_cvt_pk_bf16_f32 v202, v226, v227
	v_cvt_pk_bf16_f32 v203, v228, v229
	global_store_dword v[4:5], v202, off
	v_lshl_add_u64 v[4:5], v[4:5], 0, s[90:91]
	global_store_dword v[4:5], v203, off
	v_lshl_add_u64 v[4:5], v[4:5], 0, s[90:91]
	ds_read2_b32 v[222:223], v201 offset1:1
	ds_read2_b32 v[224:225], v201 offset0:129 offset1:130
	v_add_u32_e32 v201, 0x408, v201
	s_waitcnt lgkmcnt(4)
	v_pk_mul_f32 v[230:231], v[230:231], s[4:5] op_sel_hi:[1,0]
	v_pk_mul_f32 v[232:233], v[232:233], s[100:101] op_sel_hi:[1,0]
	v_readlane_b32 vcc_lo, v194, 28
	v_readlane_b32 s4, v194, 30
	v_pk_mul_f32 v[230:231], v[2:3], v[230:231]
	v_pk_mul_f32 v[232:233], v[2:3], v[232:233]
	v_cvt_pk_bf16_f32 v202, v230, v231
	v_cvt_pk_bf16_f32 v203, v232, v233
	global_store_dword v[4:5], v202, off
	v_lshl_add_u64 v[4:5], v[4:5], 0, s[90:91]
	global_store_dword v[4:5], v203, off
	v_lshl_add_u64 v[4:5], v[4:5], 0, s[90:91]
	ds_read2_b32 v[226:227], v201 offset1:1
	ds_read2_b32 v[228:229], v201 offset0:129 offset1:130
	v_add_u32_e32 v201, 0x408, v201
	s_waitcnt lgkmcnt(4)
	v_pk_mul_f32 v[234:235], v[234:235], vcc op_sel_hi:[1,0]
	v_pk_mul_f32 v[236:237], v[236:237], s[4:5] op_sel_hi:[1,0]
	v_readlane_b32 s100, v194, 32
	v_readlane_b32 vcc_lo, v194, 34
	v_pk_mul_f32 v[234:235], v[2:3], v[234:235]
	v_pk_mul_f32 v[236:237], v[2:3], v[236:237]
	v_cvt_pk_bf16_f32 v202, v234, v235
	v_cvt_pk_bf16_f32 v203, v236, v237
	global_store_dword v[4:5], v202, off
	v_lshl_add_u64 v[4:5], v[4:5], 0, s[90:91]
	global_store_dword v[4:5], v203, off
	v_lshl_add_u64 v[4:5], v[4:5], 0, s[90:91]
	ds_read2_b32 v[230:231], v201 offset1:1
	ds_read2_b32 v[232:233], v201 offset0:129 offset1:130
	v_add_u32_e32 v201, 0x408, v201
	s_waitcnt lgkmcnt(4)
	v_pk_mul_f32 v[222:223], v[222:223], s[100:101] op_sel_hi:[1,0]
	v_pk_mul_f32 v[224:225], v[224:225], vcc op_sel_hi:[1,0]
	v_readlane_b32 s4, v194, 36
	v_readlane_b32 s100, v194, 38
	v_pk_mul_f32 v[222:223], v[2:3], v[222:223]
	v_pk_mul_f32 v[224:225], v[2:3], v[224:225]
	v_cvt_pk_bf16_f32 v202, v222, v223
	v_cvt_pk_bf16_f32 v203, v224, v225
	global_store_dword v[4:5], v202, off
	v_lshl_add_u64 v[4:5], v[4:5], 0, s[90:91]
	global_store_dword v[4:5], v203, off
	v_lshl_add_u64 v[4:5], v[4:5], 0, s[90:91]
	ds_read2_b32 v[234:235], v201 offset1:1
	ds_read2_b32 v[236:237], v201 offset0:129 offset1:130
	v_add_u32_e32 v201, 0x408, v201
	s_waitcnt lgkmcnt(4)
	v_pk_mul_f32 v[226:227], v[226:227], s[4:5] op_sel_hi:[1,0]
	v_pk_mul_f32 v[228:229], v[228:229], s[100:101] op_sel_hi:[1,0]
	v_readlane_b32 vcc_lo, v194, 40
	v_readlane_b32 s4, v194, 42
	v_pk_mul_f32 v[226:227], v[2:3], v[226:227]
	v_pk_mul_f32 v[228:229], v[2:3], v[228:229]
	v_cvt_pk_bf16_f32 v202, v226, v227
	v_cvt_pk_bf16_f32 v203, v228, v229
	global_store_dword v[4:5], v202, off
	v_lshl_add_u64 v[4:5], v[4:5], 0, s[90:91]
	global_store_dword v[4:5], v203, off
	v_lshl_add_u64 v[4:5], v[4:5], 0, s[90:91]
	ds_read2_b32 v[222:223], v201 offset1:1
	ds_read2_b32 v[224:225], v201 offset0:129 offset1:130
	v_add_u32_e32 v201, 0x408, v201
	s_waitcnt lgkmcnt(4)
	v_pk_mul_f32 v[230:231], v[230:231], vcc op_sel_hi:[1,0]
	v_pk_mul_f32 v[232:233], v[232:233], s[4:5] op_sel_hi:[1,0]
	v_readlane_b32 s100, v194, 44
	v_readlane_b32 vcc_lo, v194, 46
	v_pk_mul_f32 v[230:231], v[2:3], v[230:231]
	v_pk_mul_f32 v[232:233], v[2:3], v[232:233]
	v_cvt_pk_bf16_f32 v202, v230, v231
	v_cvt_pk_bf16_f32 v203, v232, v233
	global_store_dword v[4:5], v202, off
	v_lshl_add_u64 v[4:5], v[4:5], 0, s[90:91]
	global_store_dword v[4:5], v203, off
	v_lshl_add_u64 v[4:5], v[4:5], 0, s[90:91]
	ds_read2_b32 v[226:227], v201 offset1:1
	ds_read2_b32 v[228:229], v201 offset0:129 offset1:130
	v_add_u32_e32 v201, 0x408, v201
	s_waitcnt lgkmcnt(4)
	v_pk_mul_f32 v[234:235], v[234:235], s[100:101] op_sel_hi:[1,0]
	v_pk_mul_f32 v[236:237], v[236:237], vcc op_sel_hi:[1,0]
	v_readlane_b32 s4, v194, 48
	v_readlane_b32 s100, v194, 50
	v_pk_mul_f32 v[234:235], v[2:3], v[234:235]
	v_pk_mul_f32 v[236:237], v[2:3], v[236:237]
	v_cvt_pk_bf16_f32 v202, v234, v235
	v_cvt_pk_bf16_f32 v203, v236, v237
	global_store_dword v[4:5], v202, off
	v_lshl_add_u64 v[4:5], v[4:5], 0, s[90:91]
	global_store_dword v[4:5], v203, off
	v_lshl_add_u64 v[4:5], v[4:5], 0, s[90:91]
	ds_read2_b32 v[230:231], v201 offset1:1
	ds_read2_b32 v[232:233], v201 offset0:129 offset1:130
	v_add_u32_e32 v201, 0x408, v201
	s_waitcnt lgkmcnt(4)
	v_pk_mul_f32 v[222:223], v[222:223], s[4:5] op_sel_hi:[1,0]
	v_pk_mul_f32 v[224:225], v[224:225], s[100:101] op_sel_hi:[1,0]
	v_readlane_b32 vcc_lo, v194, 52
	v_readlane_b32 s4, v194, 54
	v_pk_mul_f32 v[222:223], v[2:3], v[222:223]
	v_pk_mul_f32 v[224:225], v[2:3], v[224:225]
	v_cvt_pk_bf16_f32 v202, v222, v223
	v_cvt_pk_bf16_f32 v203, v224, v225
	global_store_dword v[4:5], v202, off
	v_lshl_add_u64 v[4:5], v[4:5], 0, s[90:91]
	global_store_dword v[4:5], v203, off
	v_lshl_add_u64 v[4:5], v[4:5], 0, s[90:91]
	ds_read2_b32 v[234:235], v201 offset1:1
	ds_read2_b32 v[236:237], v201 offset0:129 offset1:130
	v_add_u32_e32 v201, 0x408, v201
	s_waitcnt lgkmcnt(4)
	v_pk_mul_f32 v[226:227], v[226:227], vcc op_sel_hi:[1,0]
	v_pk_mul_f32 v[228:229], v[228:229], s[4:5] op_sel_hi:[1,0]
	v_readlane_b32 s100, v194, 56
	v_readlane_b32 vcc_lo, v194, 58
	v_pk_mul_f32 v[226:227], v[2:3], v[226:227]
	v_pk_mul_f32 v[228:229], v[2:3], v[228:229]
	v_cvt_pk_bf16_f32 v202, v226, v227
	v_cvt_pk_bf16_f32 v203, v228, v229
	global_store_dword v[4:5], v202, off
	v_lshl_add_u64 v[4:5], v[4:5], 0, s[90:91]
	global_store_dword v[4:5], v203, off
	v_lshl_add_u64 v[4:5], v[4:5], 0, s[90:91]
	s_waitcnt lgkmcnt(2)
	v_pk_mul_f32 v[230:231], v[230:231], s[100:101] op_sel_hi:[1,0]
	v_pk_mul_f32 v[232:233], v[232:233], vcc op_sel_hi:[1,0]
	v_readlane_b32 s4, v194, 60
	v_readlane_b32 s100, v194, 62
	v_pk_mul_f32 v[230:231], v[2:3], v[230:231]
	v_pk_mul_f32 v[232:233], v[2:3], v[232:233]
	v_cvt_pk_bf16_f32 v202, v230, v231
	v_cvt_pk_bf16_f32 v203, v232, v233
	global_store_dword v[4:5], v202, off
	v_lshl_add_u64 v[4:5], v[4:5], 0, s[90:91]
	global_store_dword v[4:5], v203, off
	v_lshl_add_u64 v[4:5], v[4:5], 0, s[90:91]
	s_waitcnt lgkmcnt(0)
	v_pk_mul_f32 v[234:235], v[234:235], s[4:5] op_sel_hi:[1,0]
	v_pk_mul_f32 v[236:237], v[236:237], s[100:101] op_sel_hi:[1,0]
	s_nop 1
	v_pk_mul_f32 v[234:235], v[2:3], v[234:235]
	v_pk_mul_f32 v[236:237], v[2:3], v[236:237]
	v_cvt_pk_bf16_f32 v202, v234, v235
	v_cvt_pk_bf16_f32 v203, v236, v237
	global_store_dword v[4:5], v202, off
	v_lshl_add_u64 v[4:5], v[4:5], 0, s[90:91]
	global_store_dword v[4:5], v203, off
	v_lshl_add_u64 v[4:5], v[4:5], 0, s[90:91]
	s_movk_i32 s4, 0x4080
	s_branch .LBB0_1156
